# k19_scanqk
# baseline (speedup 1.0000x reference)
; DI f32x16 mfma32(bf16x8 a, bf16x8 b, f32x16 c) { return __builtin_amdgcn_mfma_f32_32x32x16_bf16(a, b, c, 0, 0, 0); }
; DI f32x16 fzero() { f32x16 z; for (int i = 0; i < 16; ++i) z[i] = 0.f; return z; }
; DI void phase_gla_scan(const Params& p, char* smem) {
;     ...
;       f32x16 acc = fzero();
;       if (!(mt == 0 && nt == 1)) {
; #pragma unroll
;         for (int ks = 0; ks < 8; ++ks) {
;           const bf16x8 a = *(const bf16x8*)(Qs + (mt * 32 + r) * 136 + ks * 16 + h * 8);
;           const bf16x8 bb = *(const bf16x8*)(Ks + (nt * 32 + r) * 136 + ks * 16 + h * 8);
;           acc = mfma32(a, bb, acc);
;         }
;       }
.LBB0_596:
	v_mov_b32_e32 v0, 0
	v_mov_b32_e32 v1, 0
	v_mov_b32_e32 v2, 0
	v_mov_b32_e32 v3, 0
	v_mov_b32_e32 v4, 0
	v_mov_b32_e32 v5, 0
	v_mov_b32_e32 v6, 0
	v_mov_b32_e32 v7, 0
	v_mov_b32_e32 v8, 0
	v_mov_b32_e32 v9, 0
	v_mov_b32_e32 v10, 0
	v_mov_b32_e32 v11, 0
	v_mov_b32_e32 v12, 0
	v_mov_b32_e32 v13, 0
	v_mov_b32_e32 v14, 0
	v_mov_b32_e32 v15, 0
	s_and_saveexec_b64 s[46:47], s[48:49]
	s_cbranch_execz .LBB0_598
	ds_read_b128 v[0:3], v87
	ds_read_b128 v[4:7], v119 offset:17408
	ds_read_b128 v[16:19], v87 offset:32
	ds_read_b128 v[20:23], v119 offset:17440
	ds_read_b128 v[24:27], v87 offset:64
	ds_read_b128 v[28:31], v119 offset:17472
	ds_read_b128 v[230:233], v87 offset:96
	ds_read_b128 v[234:237], v119 offset:17504
	ds_read_b128 v[238:241], v87 offset:128
	ds_read_b128 v[242:245], v119 offset:17536
	ds_read_b128 v[246:249], v87 offset:160
	ds_read_b128 v[250:253], v119 offset:17568
	ds_read_b128 v[200:203], v87 offset:192
	ds_read_b128 v[204:207], v119 offset:17600
	ds_read_b128 v[208:211], v87 offset:224
	ds_read_b128 v[170:173], v119 offset:17632
	s_waitcnt lgkmcnt(14)
	v_mfma_f32_32x32x16_bf16 v[0:15], v[0:3], v[4:7], 0
	s_waitcnt lgkmcnt(12)
	v_mfma_f32_32x32x16_bf16 v[0:15], v[16:19], v[20:23], v[0:15]
	s_waitcnt lgkmcnt(10)
	v_mfma_f32_32x32x16_bf16 v[0:15], v[24:27], v[28:31], v[0:15]
	s_waitcnt lgkmcnt(8)
	v_mfma_f32_32x32x16_bf16 v[0:15], v[230:233], v[234:237], v[0:15]
	s_waitcnt lgkmcnt(6)
	v_mfma_f32_32x32x16_bf16 v[0:15], v[238:241], v[242:245], v[0:15]
	s_waitcnt lgkmcnt(4)
	v_mfma_f32_32x32x16_bf16 v[0:15], v[246:249], v[250:253], v[0:15]
	s_waitcnt lgkmcnt(2)
	v_mfma_f32_32x32x16_bf16 v[0:15], v[200:203], v[204:207], v[0:15]
	s_waitcnt lgkmcnt(0)
	v_mfma_f32_32x32x16_bf16 v[0:15], v[208:211], v[170:173], v[0:15]
